# sc1 write-through also on the MLP-up (w1) output stores U; on top of eb6
# baseline (speedup 1.0000x reference)
.LBB0_1545:
	v_lshl_add_u32 v136, s46, 8, v0
	v_max_f32_e32 v126, v126, v126
	v_ashrrev_i32_e32 v137, 31, v136
	v_max_f32_e32 v126, 0, v126
	v_max_f32_e32 v127, v127, v127
	v_max_f32_e32 v128, v128, v128
	v_lshl_or_b32 v134, s67, 8, v17
	v_lshlrev_b64 v[138:139], 14, v[136:137]
	v_mul_f32_e32 v137, v126, v126
	v_max_f32_e32 v126, v131, v131
	v_max_f32_e32 v127, 0, v127
	v_max_f32_e32 v128, 0, v128
	v_ashrrev_i32_e32 v135, 31, v134
	v_max_f32_e32 v130, v130, v130
	v_max_f32_e32 v126, 0, v126
	v_mul_f32_e32 v131, v127, v127
	v_max_f32_e32 v127, v132, v132
	v_mul_f32_e32 v132, v128, v128
	v_max_f32_e32 v128, v133, v133
	v_max_f32_e32 v129, v129, v129
	v_lshl_add_u64 v[138:139], s[6:7], 0, v[138:139]
	v_lshlrev_b64 v[140:141], 1, v[134:135]
	v_max_f32_e32 v130, 0, v130
	v_mul_f32_e32 v126, v126, v126
	v_max_f32_e32 v127, 0, v127
	v_max_f32_e32 v128, 0, v128
	v_max_f32_e32 v129, 0, v129
	v_max_f32_e32 v118, v118, v118
	v_lshl_add_u64 v[134:135], v[138:139], 0, v[140:141]
	v_mul_f32_e32 v130, v130, v130
	v_mul_f32_e32 v127, v127, v127
	v_mul_f32_e32 v128, v128, v128
	v_mul_f32_e32 v129, v129, v129
	v_cvt_pk_bf16_f32 v126, v130, v126
	v_max_f32_e32 v118, 0, v118
	v_max_f32_e32 v119, v119, v119
	v_max_f32_e32 v120, v120, v120
	v_cvt_pk_bf16_f32 v127, v127, v128
	v_cvt_pk_bf16_f32 v128, v137, v131
	v_cvt_pk_bf16_f32 v129, v132, v129
	global_store_dwordx4 v[134:135], v[126:129], off sc1
	v_max_f32_e32 v119, 0, v119
	v_max_f32_e32 v120, 0, v120
	v_mul_f32_e32 v126, v118, v118
	v_max_f32_e32 v118, v123, v123
	v_max_f32_e32 v122, v122, v122
	v_max_f32_e32 v118, 0, v118
	v_mul_f32_e32 v123, v119, v119
	v_max_f32_e32 v119, v124, v124
	v_mul_f32_e32 v124, v120, v120
	v_max_f32_e32 v120, v125, v125
	v_max_f32_e32 v121, v121, v121
	v_max_f32_e32 v122, 0, v122
	v_mul_f32_e32 v118, v118, v118
	v_max_f32_e32 v119, 0, v119
	v_max_f32_e32 v120, 0, v120
	v_max_f32_e32 v121, 0, v121
	v_mul_f32_e32 v122, v122, v122
	v_mul_f32_e32 v119, v119, v119
	v_mul_f32_e32 v120, v120, v120
	v_mul_f32_e32 v121, v121, v121
	v_cvt_pk_bf16_f32 v118, v122, v118
	v_max_f32_e32 v110, v110, v110
	v_cvt_pk_bf16_f32 v119, v119, v120
	v_cvt_pk_bf16_f32 v120, v126, v123
	v_cvt_pk_bf16_f32 v121, v124, v121
	global_store_dwordx4 v[134:135], v[118:121], off offset:256 sc1
	v_max_f32_e32 v110, 0, v110
	v_max_f32_e32 v111, v111, v111
	v_or_b32_e32 v118, 16, v136
	v_max_f32_e32 v112, v112, v112
	v_ashrrev_i32_e32 v119, 31, v118
	v_mul_f32_e32 v120, v110, v110
	v_max_f32_e32 v110, v115, v115
	v_max_f32_e32 v111, 0, v111
	v_max_f32_e32 v112, 0, v112
	v_lshlrev_b64 v[118:119], 14, v[118:119]
	v_max_f32_e32 v114, v114, v114
	v_max_f32_e32 v110, 0, v110
	v_mul_f32_e32 v115, v111, v111
	v_max_f32_e32 v111, v116, v116
	v_mul_f32_e32 v116, v112, v112
	v_max_f32_e32 v112, v117, v117
	v_max_f32_e32 v113, v113, v113
	v_lshl_add_u64 v[118:119], s[6:7], 0, v[118:119]
	v_max_f32_e32 v114, 0, v114
	v_mul_f32_e32 v110, v110, v110
	v_max_f32_e32 v111, 0, v111
	v_max_f32_e32 v112, 0, v112
	v_max_f32_e32 v113, 0, v113
	v_max_f32_e32 v102, v102, v102
	v_lshl_add_u64 v[118:119], v[118:119], 0, v[140:141]
	v_mul_f32_e32 v114, v114, v114
	v_mul_f32_e32 v111, v111, v111
	v_mul_f32_e32 v112, v112, v112
	v_mul_f32_e32 v113, v113, v113
	v_cvt_pk_bf16_f32 v110, v114, v110
	v_max_f32_e32 v102, 0, v102
	v_max_f32_e32 v103, v103, v103
	v_max_f32_e32 v104, v104, v104
	v_cvt_pk_bf16_f32 v111, v111, v112
	v_cvt_pk_bf16_f32 v112, v120, v115
	v_cvt_pk_bf16_f32 v113, v116, v113
	global_store_dwordx4 v[118:119], v[110:113], off sc1
	v_max_f32_e32 v103, 0, v103
	v_max_f32_e32 v104, 0, v104
	v_mul_f32_e32 v110, v102, v102
	v_max_f32_e32 v102, v107, v107
	v_max_f32_e32 v106, v106, v106
	v_max_f32_e32 v102, 0, v102
	v_mul_f32_e32 v107, v103, v103
	v_max_f32_e32 v103, v108, v108
	v_mul_f32_e32 v108, v104, v104
	v_max_f32_e32 v104, v109, v109
	v_max_f32_e32 v105, v105, v105
	v_max_f32_e32 v106, 0, v106
	v_mul_f32_e32 v102, v102, v102
	v_max_f32_e32 v103, 0, v103
	v_max_f32_e32 v104, 0, v104
	v_max_f32_e32 v105, 0, v105
	v_mul_f32_e32 v106, v106, v106
	v_mul_f32_e32 v103, v103, v103
	v_mul_f32_e32 v104, v104, v104
	v_mul_f32_e32 v105, v105, v105
	v_cvt_pk_bf16_f32 v102, v106, v102
	v_max_f32_e32 v94, v94, v94
	v_cvt_pk_bf16_f32 v103, v103, v104
	v_cvt_pk_bf16_f32 v104, v110, v107
	v_cvt_pk_bf16_f32 v105, v108, v105
	global_store_dwordx4 v[118:119], v[102:105], off offset:256 sc1
	v_max_f32_e32 v94, 0, v94
	v_max_f32_e32 v95, v95, v95
	v_or_b32_e32 v102, 32, v136
	v_max_f32_e32 v96, v96, v96
	v_ashrrev_i32_e32 v103, 31, v102
	v_mul_f32_e32 v104, v94, v94
	v_max_f32_e32 v94, v99, v99
	v_max_f32_e32 v95, 0, v95
	v_max_f32_e32 v96, 0, v96
	v_lshlrev_b64 v[102:103], 14, v[102:103]
	v_max_f32_e32 v98, v98, v98
	v_max_f32_e32 v94, 0, v94
	v_mul_f32_e32 v99, v95, v95
	v_max_f32_e32 v95, v100, v100
	v_mul_f32_e32 v100, v96, v96
	v_max_f32_e32 v96, v101, v101
	v_max_f32_e32 v97, v97, v97
	v_lshl_add_u64 v[102:103], s[6:7], 0, v[102:103]
	v_max_f32_e32 v98, 0, v98
	v_mul_f32_e32 v94, v94, v94
	v_max_f32_e32 v95, 0, v95
	v_max_f32_e32 v96, 0, v96
	v_max_f32_e32 v97, 0, v97
	v_max_f32_e32 v86, v86, v86
	v_lshl_add_u64 v[102:103], v[102:103], 0, v[140:141]
	v_mul_f32_e32 v98, v98, v98
	v_mul_f32_e32 v95, v95, v95
	v_mul_f32_e32 v96, v96, v96
	v_mul_f32_e32 v97, v97, v97
	v_cvt_pk_bf16_f32 v94, v98, v94
	v_max_f32_e32 v86, 0, v86
	v_max_f32_e32 v87, v87, v87
	v_max_f32_e32 v88, v88, v88
	v_cvt_pk_bf16_f32 v95, v95, v96
	v_cvt_pk_bf16_f32 v96, v104, v99
	v_cvt_pk_bf16_f32 v97, v100, v97
	global_store_dwordx4 v[102:103], v[94:97], off sc1
	v_max_f32_e32 v87, 0, v87
	v_max_f32_e32 v88, 0, v88
	v_mul_f32_e32 v94, v86, v86
	v_max_f32_e32 v86, v91, v91
	v_max_f32_e32 v90, v90, v90
	v_max_f32_e32 v86, 0, v86
	v_mul_f32_e32 v91, v87, v87
	v_max_f32_e32 v87, v92, v92
	v_mul_f32_e32 v92, v88, v88
	v_max_f32_e32 v88, v93, v93
	v_max_f32_e32 v89, v89, v89
	v_max_f32_e32 v90, 0, v90
	v_mul_f32_e32 v86, v86, v86
	v_max_f32_e32 v87, 0, v87
	v_max_f32_e32 v88, 0, v88
	v_max_f32_e32 v89, 0, v89
	v_mul_f32_e32 v90, v90, v90
	v_mul_f32_e32 v87, v87, v87
	v_mul_f32_e32 v88, v88, v88
	v_mul_f32_e32 v89, v89, v89
	v_cvt_pk_bf16_f32 v86, v90, v86
	v_max_f32_e32 v78, v78, v78
	v_cvt_pk_bf16_f32 v87, v87, v88
	v_cvt_pk_bf16_f32 v88, v94, v91
	v_cvt_pk_bf16_f32 v89, v92, v89
	global_store_dwordx4 v[102:103], v[86:89], off offset:256 sc1
	v_max_f32_e32 v78, 0, v78
	v_max_f32_e32 v79, v79, v79
	v_or_b32_e32 v86, 48, v136
	v_max_f32_e32 v80, v80, v80
	v_ashrrev_i32_e32 v87, 31, v86
	v_mul_f32_e32 v88, v78, v78
	v_max_f32_e32 v78, v83, v83
	v_max_f32_e32 v79, 0, v79
	v_max_f32_e32 v80, 0, v80
	v_lshlrev_b64 v[86:87], 14, v[86:87]
	v_max_f32_e32 v82, v82, v82
	v_max_f32_e32 v78, 0, v78
	v_mul_f32_e32 v83, v79, v79
	v_max_f32_e32 v79, v84, v84
	v_mul_f32_e32 v84, v80, v80
	v_max_f32_e32 v80, v85, v85
	v_max_f32_e32 v81, v81, v81
	v_lshl_add_u64 v[86:87], s[6:7], 0, v[86:87]
	v_max_f32_e32 v82, 0, v82
	v_mul_f32_e32 v78, v78, v78
	v_max_f32_e32 v79, 0, v79
	v_max_f32_e32 v80, 0, v80
	v_max_f32_e32 v81, 0, v81
	v_max_f32_e32 v70, v70, v70
	v_max_f32_e32 v71, v71, v71
	v_max_f32_e32 v72, v72, v72
	v_lshl_add_u64 v[86:87], v[86:87], 0, v[140:141]
	v_mul_f32_e32 v82, v82, v82
	v_mul_f32_e32 v79, v79, v79
	v_mul_f32_e32 v80, v80, v80
	v_mul_f32_e32 v81, v81, v81
	v_cvt_pk_bf16_f32 v78, v82, v78
	v_max_f32_e32 v70, 0, v70
	v_max_f32_e32 v71, 0, v71
	v_max_f32_e32 v72, 0, v72
	v_cvt_pk_bf16_f32 v79, v79, v80
	v_cvt_pk_bf16_f32 v80, v88, v83
	v_cvt_pk_bf16_f32 v81, v84, v81
	global_store_dwordx4 v[86:87], v[78:81], off sc1
	v_max_f32_e32 v74, v74, v74
	v_max_f32_e32 v73, v73, v73
	v_mul_f32_e32 v78, v70, v70
	v_max_f32_e32 v70, v75, v75
	v_mul_f32_e32 v75, v71, v71
	v_max_f32_e32 v71, v76, v76
	v_mul_f32_e32 v76, v72, v72
	v_max_f32_e32 v72, v77, v77
	v_max_f32_e32 v70, 0, v70
	v_max_f32_e32 v71, 0, v71
	v_max_f32_e32 v72, 0, v72
	v_max_f32_e32 v74, 0, v74
	v_mul_f32_e32 v70, v70, v70
	v_mul_f32_e32 v71, v71, v71
	v_max_f32_e32 v73, 0, v73
	v_mul_f32_e32 v72, v72, v72
	v_max_f32_e32 v62, v62, v62
	v_mul_f32_e32 v74, v74, v74
	v_mul_f32_e32 v73, v73, v73
	v_cvt_pk_bf16_f32 v70, v74, v70
	v_cvt_pk_bf16_f32 v71, v71, v72
	v_cvt_pk_bf16_f32 v72, v78, v75
	v_max_f32_e32 v62, 0, v62
	v_max_f32_e32 v63, v63, v63
	v_max_f32_e32 v64, v64, v64
	v_cvt_pk_bf16_f32 v73, v76, v73
	global_store_dwordx4 v[86:87], v[70:73], off offset:256 sc1
	v_max_f32_e32 v66, v66, v66
	v_max_f32_e32 v63, 0, v63
	v_mul_f32_e32 v72, v62, v62
	v_max_f32_e32 v62, v67, v67
	v_max_f32_e32 v64, 0, v64
	v_max_f32_e32 v66, 0, v66
	v_max_f32_e32 v62, 0, v62
	v_mul_f32_e32 v67, v63, v63
	v_max_f32_e32 v63, v68, v68
	v_mul_f32_e32 v68, v64, v64
	v_max_f32_e32 v64, v69, v69
	v_mul_f32_e32 v66, v66, v66
	v_mul_f32_e32 v62, v62, v62
	v_max_f32_e32 v63, 0, v63
	v_max_f32_e32 v64, 0, v64
	v_max_f32_e32 v65, v65, v65
	s_mov_b32 s11, 0x200000
	v_mul_f32_e32 v63, v63, v63
	v_max_f32_e32 v65, 0, v65
	v_mul_f32_e32 v64, v64, v64
	v_cvt_pk_bf16_f32 v62, v66, v62
	v_add_co_u32_e32 v66, vcc, s11, v134
	v_max_f32_e32 v54, v54, v54
	v_max_f32_e32 v55, v55, v55
	v_max_f32_e32 v56, v56, v56
	v_mul_f32_e32 v65, v65, v65
	v_cvt_pk_bf16_f32 v63, v63, v64
	v_cvt_pk_bf16_f32 v64, v72, v67
	v_addc_co_u32_e32 v67, vcc, 0, v135, vcc
	v_max_f32_e32 v54, 0, v54
	v_max_f32_e32 v55, 0, v55
	v_max_f32_e32 v56, 0, v56
	v_cvt_pk_bf16_f32 v65, v68, v65
	global_store_dwordx4 v[66:67], v[62:65], off sc1
	v_max_f32_e32 v58, v58, v58
	v_max_f32_e32 v57, v57, v57
	v_mul_f32_e32 v62, v54, v54
	v_max_f32_e32 v54, v59, v59
	v_mul_f32_e32 v59, v55, v55
	v_max_f32_e32 v55, v60, v60
	v_mul_f32_e32 v60, v56, v56
	v_max_f32_e32 v56, v61, v61
	v_max_f32_e32 v54, 0, v54
	v_max_f32_e32 v55, 0, v55
	v_max_f32_e32 v56, 0, v56
	s_mov_b64 s[48:49], 0x200000
	v_max_f32_e32 v58, 0, v58
	v_mul_f32_e32 v54, v54, v54
	v_mul_f32_e32 v55, v55, v55
	v_max_f32_e32 v57, 0, v57
	v_mul_f32_e32 v56, v56, v56
	v_max_f32_e32 v46, v46, v46
	v_lshl_add_u64 v[70:71], v[134:135], 0, s[48:49]
	v_mul_f32_e32 v58, v58, v58
	v_mul_f32_e32 v57, v57, v57
	v_cvt_pk_bf16_f32 v54, v58, v54
	v_cvt_pk_bf16_f32 v55, v55, v56
	v_cvt_pk_bf16_f32 v56, v62, v59
	v_max_f32_e32 v46, 0, v46
	v_max_f32_e32 v47, v47, v47
	v_max_f32_e32 v48, v48, v48
	v_cvt_pk_bf16_f32 v57, v60, v57
	global_store_dwordx4 v[70:71], v[54:57], off offset:256 sc1
	v_max_f32_e32 v50, v50, v50
	v_max_f32_e32 v47, 0, v47
	v_mul_f32_e32 v56, v46, v46
	v_max_f32_e32 v46, v51, v51
	v_max_f32_e32 v48, 0, v48
	v_max_f32_e32 v50, 0, v50
	v_max_f32_e32 v46, 0, v46
	v_mul_f32_e32 v51, v47, v47
	v_max_f32_e32 v47, v52, v52
	v_mul_f32_e32 v52, v48, v48
	v_max_f32_e32 v48, v53, v53
	v_mul_f32_e32 v50, v50, v50
	v_mul_f32_e32 v46, v46, v46
	v_max_f32_e32 v47, 0, v47
	v_max_f32_e32 v48, 0, v48
	v_max_f32_e32 v49, v49, v49
	s_mov_b32 s11, 0x240000
	v_mul_f32_e32 v47, v47, v47
	v_max_f32_e32 v49, 0, v49
	v_mul_f32_e32 v48, v48, v48
	v_cvt_pk_bf16_f32 v46, v50, v46
	v_add_co_u32_e32 v50, vcc, s11, v134
	v_max_f32_e32 v38, v38, v38
	v_max_f32_e32 v39, v39, v39
	v_max_f32_e32 v40, v40, v40
	v_mul_f32_e32 v49, v49, v49
	v_cvt_pk_bf16_f32 v47, v47, v48
	v_cvt_pk_bf16_f32 v48, v56, v51
	v_addc_co_u32_e32 v51, vcc, 0, v135, vcc
	v_max_f32_e32 v38, 0, v38
	v_max_f32_e32 v39, 0, v39
	v_max_f32_e32 v40, 0, v40
	v_cvt_pk_bf16_f32 v49, v52, v49
	global_store_dwordx4 v[50:51], v[46:49], off sc1
	v_max_f32_e32 v42, v42, v42
	v_max_f32_e32 v41, v41, v41
	v_mul_f32_e32 v46, v38, v38
	v_max_f32_e32 v38, v43, v43
	v_mul_f32_e32 v43, v39, v39
	v_max_f32_e32 v39, v44, v44
	v_mul_f32_e32 v44, v40, v40
	v_max_f32_e32 v40, v45, v45
	v_max_f32_e32 v38, 0, v38
	v_max_f32_e32 v39, 0, v39
	v_max_f32_e32 v40, 0, v40
	s_mov_b64 s[48:49], 0x240000
	v_max_f32_e32 v42, 0, v42
	v_mul_f32_e32 v38, v38, v38
	v_mul_f32_e32 v39, v39, v39
	v_max_f32_e32 v41, 0, v41
	v_mul_f32_e32 v40, v40, v40
	v_max_f32_e32 v30, v30, v30
	v_lshl_add_u64 v[54:55], v[134:135], 0, s[48:49]
	v_mul_f32_e32 v42, v42, v42
	v_mul_f32_e32 v41, v41, v41
	v_cvt_pk_bf16_f32 v38, v42, v38
	v_cvt_pk_bf16_f32 v39, v39, v40
	v_cvt_pk_bf16_f32 v40, v46, v43
	v_max_f32_e32 v30, 0, v30
	v_max_f32_e32 v31, v31, v31
	v_max_f32_e32 v32, v32, v32
	v_cvt_pk_bf16_f32 v41, v44, v41
	global_store_dwordx4 v[54:55], v[38:41], off offset:256 sc1
	v_max_f32_e32 v34, v34, v34
	v_max_f32_e32 v31, 0, v31
	v_mul_f32_e32 v40, v30, v30
	v_max_f32_e32 v30, v35, v35
	v_max_f32_e32 v32, 0, v32
	v_max_f32_e32 v34, 0, v34
	v_max_f32_e32 v30, 0, v30
	v_mul_f32_e32 v35, v31, v31
	v_max_f32_e32 v31, v36, v36
	v_mul_f32_e32 v36, v32, v32
	v_max_f32_e32 v32, v37, v37
	v_mul_f32_e32 v34, v34, v34
	v_mul_f32_e32 v30, v30, v30
	v_max_f32_e32 v31, 0, v31
	v_max_f32_e32 v32, 0, v32
	v_max_f32_e32 v33, v33, v33
	s_mov_b32 s11, 0x280000
	v_mul_f32_e32 v31, v31, v31
	v_max_f32_e32 v33, 0, v33
	v_mul_f32_e32 v32, v32, v32
	v_cvt_pk_bf16_f32 v30, v34, v30
	v_add_co_u32_e32 v34, vcc, s11, v134
	v_max_f32_e32 v22, v22, v22
	v_max_f32_e32 v23, v23, v23
	v_max_f32_e32 v24, v24, v24
	v_mul_f32_e32 v33, v33, v33
	v_cvt_pk_bf16_f32 v31, v31, v32
	v_cvt_pk_bf16_f32 v32, v40, v35
	v_addc_co_u32_e32 v35, vcc, 0, v135, vcc
	v_max_f32_e32 v22, 0, v22
	v_max_f32_e32 v23, 0, v23
	v_max_f32_e32 v24, 0, v24
	v_cvt_pk_bf16_f32 v33, v36, v33
	global_store_dwordx4 v[34:35], v[30:33], off sc1
	v_max_f32_e32 v26, v26, v26
	v_max_f32_e32 v25, v25, v25
	v_mul_f32_e32 v30, v22, v22
	v_max_f32_e32 v22, v27, v27
	v_mul_f32_e32 v27, v23, v23
	v_max_f32_e32 v23, v28, v28
	v_mul_f32_e32 v28, v24, v24
	v_max_f32_e32 v24, v29, v29
	v_max_f32_e32 v22, 0, v22
	v_max_f32_e32 v23, 0, v23
	v_max_f32_e32 v24, 0, v24
	s_mov_b64 s[48:49], 0x280000
	v_max_f32_e32 v26, 0, v26
	v_mul_f32_e32 v22, v22, v22
	v_mul_f32_e32 v23, v23, v23
	v_max_f32_e32 v25, 0, v25
	v_mul_f32_e32 v24, v24, v24
	v_max_f32_e32 v10, v10, v10
	v_lshl_add_u64 v[38:39], v[134:135], 0, s[48:49]
	v_mul_f32_e32 v26, v26, v26
	v_mul_f32_e32 v25, v25, v25
	v_cvt_pk_bf16_f32 v22, v26, v22
	v_cvt_pk_bf16_f32 v23, v23, v24
	v_cvt_pk_bf16_f32 v24, v30, v27
	v_max_f32_e32 v10, 0, v10
	v_max_f32_e32 v11, v11, v11
	v_max_f32_e32 v12, v12, v12
	v_cvt_pk_bf16_f32 v25, v28, v25
	global_store_dwordx4 v[38:39], v[22:25], off offset:256 sc1
	v_max_f32_e32 v18, v18, v18
	v_max_f32_e32 v11, 0, v11
	v_mul_f32_e32 v24, v10, v10
	v_max_f32_e32 v10, v19, v19
	v_max_f32_e32 v12, 0, v12
	v_max_f32_e32 v18, 0, v18
	v_max_f32_e32 v10, 0, v10
	v_mul_f32_e32 v19, v11, v11
	v_max_f32_e32 v11, v20, v20
	v_mul_f32_e32 v20, v12, v12
	v_max_f32_e32 v12, v21, v21
	v_mul_f32_e32 v18, v18, v18
	v_mul_f32_e32 v10, v10, v10
	v_max_f32_e32 v11, 0, v11
	v_max_f32_e32 v12, 0, v12
	v_max_f32_e32 v13, v13, v13
	s_mov_b32 s11, 0x2c0000
	v_mul_f32_e32 v11, v11, v11
	v_max_f32_e32 v13, 0, v13
	v_mul_f32_e32 v12, v12, v12
	v_cvt_pk_bf16_f32 v10, v18, v10
	v_add_co_u32_e32 v18, vcc, s11, v134
	v_max_f32_e32 v2, v2, v2
	v_max_f32_e32 v3, v3, v3
	v_max_f32_e32 v4, v4, v4
	v_mul_f32_e32 v13, v13, v13
	v_cvt_pk_bf16_f32 v11, v11, v12
	v_cvt_pk_bf16_f32 v12, v24, v19
	v_addc_co_u32_e32 v19, vcc, 0, v135, vcc
	v_max_f32_e32 v2, 0, v2
	v_max_f32_e32 v3, 0, v3
	v_max_f32_e32 v4, 0, v4
	v_cvt_pk_bf16_f32 v13, v20, v13
	global_store_dwordx4 v[18:19], v[10:13], off sc1
	v_max_f32_e32 v5, v5, v5
	s_mov_b64 s[48:49], 0x2c0000
	v_mul_f32_e32 v10, v2, v2
	v_max_f32_e32 v2, v7, v7
	v_mul_f32_e32 v7, v3, v3
	v_max_f32_e32 v3, v8, v8
	v_mul_f32_e32 v8, v4, v4
	v_max_f32_e32 v4, v9, v9
	v_max_f32_e32 v6, v6, v6
	v_max_f32_e32 v2, 0, v2
	v_max_f32_e32 v3, 0, v3
	v_max_f32_e32 v4, 0, v4
	v_max_f32_e32 v5, 0, v5
	v_lshl_add_u64 v[22:23], v[134:135], 0, s[48:49]
	v_max_f32_e32 v6, 0, v6
	v_mul_f32_e32 v2, v2, v2
	v_mul_f32_e32 v3, v3, v3
	v_mul_f32_e32 v4, v4, v4
	v_mul_f32_e32 v5, v5, v5
	s_andn2_b64 vcc, exec, s[40:41]
	s_mov_b64 s[40:41], -1
	v_mul_f32_e32 v6, v6, v6
	v_cvt_pk_bf16_f32 v2, v6, v2
	v_cvt_pk_bf16_f32 v3, v3, v4
	v_cvt_pk_bf16_f32 v4, v10, v7
	v_cvt_pk_bf16_f32 v5, v8, v5
	global_store_dwordx4 v[22:23], v[2:5], off offset:256 sc1
	s_cbranch_vccnz .LBB0_1523
	s_andn2_b64 vcc, exec, s[4:5]
	s_cbranch_vccnz .LBB0_1522
	s_barrier
	s_branch .LBB0_1522
